# speedup vs baseline: 1.0358x; 1.0039x over previous
; #define SBAR() __builtin_amdgcn_sched_barrier(0)
; #define TRQ(D0) const s16x4 l0_##D0 = tr_read<v_rd_off(D0, 2 * H, 0)>(vb), h0_##D0 = tr_read<v_rd_off(D0, 2 * H, 1)>(vb), \
;                             l1_##D0 = tr_read<v_rd_off(D0, 2 * H + 1, 0)>(vb), h1_##D0 = tr_read<v_rd_off(D0, 2 * H + 1, 1)>(vb)
; template <int H> __device__ __forceinline__ void pv_half(f32x16* o, int vb, bf16x8 paA, bf16x8 paB) {
;     ...
;   TRQ(0); TRQ(1); TRQ(2); TRQ(3);
;     ...
;   asm volatile("s_waitcnt lgkmcnt(0)" ::: "memory"); SBAR();
;     ...
;   o[0] = __builtin_amdgcn_mfma_f32_32x32x16_bf16(paA, PK(l0_0, h0_0), o[0], 0, 0, 0);
;   o[1] = __builtin_amdgcn_mfma_f32_32x32x16_bf16(paA, PK(l0_1, h0_1), o[1], 0, 0, 0);
;   o[2] = __builtin_amdgcn_mfma_f32_32x32x16_bf16(paA, PK(l0_2, h0_2), o[2], 0, 0, 0);
;   o[3] = __builtin_amdgcn_mfma_f32_32x32x16_bf16(paA, PK(l0_3, h0_3), o[3], 0, 0, 0);
;   o[0] = __builtin_amdgcn_mfma_f32_32x32x16_bf16(paB, PK(l1_0, h1_0), o[0], 0, 0, 0);
;   o[1] = __builtin_amdgcn_mfma_f32_32x32x16_bf16(paB, PK(l1_1, h1_1), o[1], 0, 0, 0);
;   o[2] = __builtin_amdgcn_mfma_f32_32x32x16_bf16(paB, PK(l1_2, h1_2), o[2], 0, 0, 0);
;   o[3] = __builtin_amdgcn_mfma_f32_32x32x16_bf16(paB, PK(l1_3, h1_3), o[3], 0, 0, 0);
;     ...
; }
; template <int MODE>
; __device__ __forceinline__ void nsa_single(const Params& p, const LaneId& L, int q0, int g, int ntiles, int first, char* smem, const bf16x8* qr, float gate, f32x16* o) {
;     ...
;     NSA_SHALF(0);
;     NSA_SHALF(1);
.Lsel_nr:
	v_sub_f32_e32 v242, v250, v165
	v_sub_f32_e32 v249, v251, v165
	s_nop 0
	v_fmamk_f32 v68, v68, 0x3e0293ee, v242
	v_fmamk_f32 v69, v69, 0x3e0293ee, v242
	v_fmamk_f32 v70, v70, 0x3e0293ee, v242
	v_fmamk_f32 v71, v71, 0x3e0293ee, v242
	v_fmamk_f32 v72, v72, 0x3e0293ee, v242
	v_fmamk_f32 v73, v73, 0x3e0293ee, v242
	v_fmamk_f32 v74, v74, 0x3e0293ee, v242
	v_fmamk_f32 v75, v75, 0x3e0293ee, v242
	v_fmamk_f32 v76, v76, 0x3e0293ee, v242
	v_fmamk_f32 v77, v77, 0x3e0293ee, v242
	v_fmamk_f32 v78, v78, 0x3e0293ee, v242
	v_fmamk_f32 v79, v79, 0x3e0293ee, v242
	v_fmamk_f32 v80, v80, 0x3e0293ee, v242
	v_fmamk_f32 v81, v81, 0x3e0293ee, v242
	v_fmamk_f32 v82, v82, 0x3e0293ee, v242
	v_fmamk_f32 v83, v83, 0x3e0293ee, v242
	v_exp_f32_e32 v68, v68
	v_exp_f32_e32 v69, v69
	v_exp_f32_e32 v70, v70
	v_exp_f32_e32 v71, v71
	v_exp_f32_e32 v72, v72
	v_exp_f32_e32 v73, v73
	v_exp_f32_e32 v74, v74
	v_exp_f32_e32 v75, v75
	v_exp_f32_e32 v76, v76
	v_exp_f32_e32 v77, v77
	v_exp_f32_e32 v78, v78
	v_exp_f32_e32 v79, v79
	v_exp_f32_e32 v80, v80
	v_exp_f32_e32 v81, v81
	v_exp_f32_e32 v82, v82
	v_exp_f32_e32 v83, v83
	v_cvt_pk_bf16_f32 v168, v68, v69
	v_cvt_pk_bf16_f32 v169, v70, v71
	v_cvt_pk_bf16_f32 v170, v72, v73
	v_cvt_pk_bf16_f32 v171, v74, v75
	v_cvt_pk_bf16_f32 v172, v76, v77
	v_cvt_pk_bf16_f32 v173, v78, v79
	v_cvt_pk_bf16_f32 v174, v80, v81
	v_cvt_pk_bf16_f32 v175, v82, v83
	s_waitcnt lgkmcnt(0)
	s_nop 0
	v_permlane32_swap_b32_e32 v168, v170
	v_permlane32_swap_b32_e32 v169, v171
	v_permlane32_swap_b32_e32 v172, v174
	v_permlane32_swap_b32_e32 v173, v175
	s_nop 1
	v_mfma_f32_32x32x16_bf16 v[52:67], v[168:171], v[84:87], v[52:67]
	ds_read_b64_tr_b16 v[84:85], v248 offset:8192
	ds_read_b64_tr_b16 v[86:87], v248 offset:10240
	v_fmamk_f32 v210, v210, 0x3e0293ee, v249
	v_fmamk_f32 v211, v211, 0x3e0293ee, v249
	v_fmamk_f32 v212, v212, 0x3e0293ee, v249
	v_fmamk_f32 v213, v213, 0x3e0293ee, v249
	v_fmamk_f32 v214, v214, 0x3e0293ee, v249
	v_fmamk_f32 v215, v215, 0x3e0293ee, v249
	v_fmamk_f32 v216, v216, 0x3e0293ee, v249
	v_fmamk_f32 v217, v217, 0x3e0293ee, v249
	v_fmamk_f32 v218, v218, 0x3e0293ee, v249
	v_fmamk_f32 v219, v219, 0x3e0293ee, v249
	v_mfma_f32_32x32x16_bf16 v[36:51], v[168:171], v[92:95], v[36:51]
	ds_read_b64_tr_b16 v[92:93], v248 offset:8704
	ds_read_b64_tr_b16 v[94:95], v248 offset:10752
	v_fmamk_f32 v220, v220, 0x3e0293ee, v249
	v_fmamk_f32 v221, v221, 0x3e0293ee, v249
	v_fmamk_f32 v222, v222, 0x3e0293ee, v249
	v_fmamk_f32 v223, v223, 0x3e0293ee, v249
	v_fmamk_f32 v224, v224, 0x3e0293ee, v249
	v_fmamk_f32 v225, v225, 0x3e0293ee, v249
	v_exp_f32_e32 v210, v210
	v_add_f32_e32 v246, v68, v69
	v_exp_f32_e32 v211, v211
	v_add_f32_e32 v247, v70, v71
	v_mfma_f32_32x32x16_bf16 v[20:35], v[168:171], v[194:197], v[20:35]
	ds_read_b64_tr_b16 v[194:195], v248 offset:9216
	ds_read_b64_tr_b16 v[196:197], v248 offset:11264
	v_exp_f32_e32 v212, v212
	v_add_f32_e32 v246, v246, v72
	v_exp_f32_e32 v213, v213
	v_add_f32_e32 v246, v246, v73
	v_exp_f32_e32 v214, v214
	v_add_f32_e32 v247, v247, v74
	v_exp_f32_e32 v215, v215
	v_add_f32_e32 v247, v247, v75
	v_exp_f32_e32 v216, v216
	v_add_f32_e32 v246, v246, v76
	v_mfma_f32_32x32x16_bf16 v[4:19], v[168:171], v[202:205], v[4:19]
	ds_read_b64_tr_b16 v[202:203], v248 offset:9728
	ds_read_b64_tr_b16 v[204:205], v248 offset:11776
	v_exp_f32_e32 v217, v217
	v_add_f32_e32 v246, v246, v77
	v_exp_f32_e32 v218, v218
	v_add_f32_e32 v247, v247, v78
	v_exp_f32_e32 v219, v219
	v_add_f32_e32 v247, v247, v79
	v_exp_f32_e32 v220, v220
	v_add_f32_e32 v246, v246, v80
	v_exp_f32_e32 v221, v221
	v_add_f32_e32 v246, v246, v81
	v_mfma_f32_32x32x16_bf16 v[52:67], v[172:175], v[88:91], v[52:67]
	ds_read_b64_tr_b16 v[88:89], v248 offset:12288
	ds_read_b64_tr_b16 v[90:91], v248 offset:14336
	v_exp_f32_e32 v222, v222
	v_add_f32_e32 v247, v247, v82
	v_exp_f32_e32 v223, v223
	v_add_f32_e32 v247, v247, v83
	v_exp_f32_e32 v224, v224
	v_exp_f32_e32 v225, v225
	v_add_f32_e32 v246, v246, v210
	v_add_f32_e32 v246, v246, v211
	v_add_f32_e32 v247, v247, v212
	v_add_f32_e32 v247, v247, v213
	v_mfma_f32_32x32x16_bf16 v[36:51], v[172:175], v[96:99], v[36:51]
	ds_read_b64_tr_b16 v[96:97], v248 offset:12800
	ds_read_b64_tr_b16 v[98:99], v248 offset:14848
	v_add_f32_e32 v246, v246, v214
	v_add_f32_e32 v246, v246, v215
	v_add_f32_e32 v247, v247, v216
	v_add_f32_e32 v247, v247, v217
	v_add_f32_e32 v246, v246, v218
	v_add_f32_e32 v246, v246, v219
	v_add_f32_e32 v247, v247, v220
	v_add_f32_e32 v247, v247, v221
	v_add_f32_e32 v246, v246, v222
	v_add_f32_e32 v246, v246, v223
	v_mfma_f32_32x32x16_bf16 v[20:35], v[172:175], v[198:201], v[20:35]
	ds_read_b64_tr_b16 v[198:199], v248 offset:13312
	ds_read_b64_tr_b16 v[200:201], v248 offset:15360
	v_add_f32_e32 v247, v247, v224
	v_add_f32_e32 v247, v247, v225
	v_add_f32_e32 v246, v246, v247
	v_add_f32_e32 v162, v162, v246
	v_cvt_pk_bf16_f32 v68, v210, v211
	v_cvt_pk_bf16_f32 v69, v212, v213
	v_cvt_pk_bf16_f32 v70, v214, v215
	v_cvt_pk_bf16_f32 v71, v216, v217
	v_cvt_pk_bf16_f32 v72, v218, v219
	v_cvt_pk_bf16_f32 v73, v220, v221
	v_mfma_f32_32x32x16_bf16 v[4:19], v[172:175], v[206:209], v[4:19]
	ds_read_b64_tr_b16 v[206:207], v248 offset:13824
	ds_read_b64_tr_b16 v[208:209], v248 offset:15872
	v_cvt_pk_bf16_f32 v74, v222, v223
	v_cvt_pk_bf16_f32 v75, v224, v225
	v_permlane32_swap_b32_e32 v68, v70
	v_permlane32_swap_b32_e32 v69, v71
	v_permlane32_swap_b32_e32 v72, v74
	v_permlane32_swap_b32_e32 v73, v75
	s_nop 1
	s_waitcnt lgkmcnt(14)
	v_mfma_f32_32x32x16_bf16 v[52:67], v[68:71], v[84:87], v[52:67]
	s_waitcnt lgkmcnt(12)
	v_mfma_f32_32x32x16_bf16 v[36:51], v[68:71], v[92:95], v[36:51]
	s_waitcnt lgkmcnt(10)
	v_mfma_f32_32x32x16_bf16 v[20:35], v[68:71], v[194:197], v[20:35]
	s_waitcnt lgkmcnt(8)
	v_mfma_f32_32x32x16_bf16 v[4:19], v[68:71], v[202:205], v[4:19]
	s_waitcnt lgkmcnt(6)
	v_mfma_f32_32x32x16_bf16 v[52:67], v[72:75], v[88:91], v[52:67]
	s_waitcnt lgkmcnt(4)
	v_mfma_f32_32x32x16_bf16 v[36:51], v[72:75], v[96:99], v[36:51]
	s_waitcnt lgkmcnt(2)
	v_mfma_f32_32x32x16_bf16 v[20:35], v[72:75], v[198:201], v[20:35]
	s_waitcnt lgkmcnt(0)
	v_mfma_f32_32x32x16_bf16 v[4:19], v[72:75], v[206:209], v[4:19]
	s_add_i32 s26, s26, -1
	s_add_i32 s61, s61, 1
	s_addk_i32 s97, 0x4000
	s_cmp_eq_u32 s26, 0
	s_cbranch_scc1 .LBB0_335
	s_branch .LBB0_316

; #define SBAR() __builtin_amdgcn_sched_barrier(0)
; #define TRQ(D0) const s16x4 l0_##D0 = tr_read<v_rd_off(D0, 2 * H, 0)>(vb), h0_##D0 = tr_read<v_rd_off(D0, 2 * H, 1)>(vb), \
;                             l1_##D0 = tr_read<v_rd_off(D0, 2 * H + 1, 0)>(vb), h1_##D0 = tr_read<v_rd_off(D0, 2 * H + 1, 1)>(vb)
; template <int H> __device__ __forceinline__ void pv_half(f32x16* o, int vb, bf16x8 paA, bf16x8 paB) {
;     ...
;   TRQ(0); TRQ(1); TRQ(2); TRQ(3);
;     ...
;   asm volatile("s_waitcnt lgkmcnt(0)" ::: "memory"); SBAR();
;     ...
;   o[0] = __builtin_amdgcn_mfma_f32_32x32x16_bf16(paA, PK(l0_0, h0_0), o[0], 0, 0, 0);
;   o[1] = __builtin_amdgcn_mfma_f32_32x32x16_bf16(paA, PK(l0_1, h0_1), o[1], 0, 0, 0);
;   o[2] = __builtin_amdgcn_mfma_f32_32x32x16_bf16(paA, PK(l0_2, h0_2), o[2], 0, 0, 0);
;   o[3] = __builtin_amdgcn_mfma_f32_32x32x16_bf16(paA, PK(l0_3, h0_3), o[3], 0, 0, 0);
;   o[0] = __builtin_amdgcn_mfma_f32_32x32x16_bf16(paB, PK(l1_0, h1_0), o[0], 0, 0, 0);
;   o[1] = __builtin_amdgcn_mfma_f32_32x32x16_bf16(paB, PK(l1_1, h1_1), o[1], 0, 0, 0);
;   o[2] = __builtin_amdgcn_mfma_f32_32x32x16_bf16(paB, PK(l1_2, h1_2), o[2], 0, 0, 0);
;   o[3] = __builtin_amdgcn_mfma_f32_32x32x16_bf16(paB, PK(l1_3, h1_3), o[3], 0, 0, 0);
;     ...
; }
; template <int MODE>
; __device__ __forceinline__ void nsa_single(const Params& p, const LaneId& L, int q0, int g, int ntiles, int first, char* smem, const bf16x8* qr, float gate, f32x16* o) {
;     ...
;     NSA_SHALF(0);
;     NSA_SHALF(1);
.Lwin_nr:
	v_sub_f32_e32 v242, v250, v165
	v_sub_f32_e32 v249, v251, v165
	s_nop 0
	v_fmamk_f32 v68, v68, 0x3e0293ee, v242
	v_fmamk_f32 v69, v69, 0x3e0293ee, v242
	v_fmamk_f32 v70, v70, 0x3e0293ee, v242
	v_fmamk_f32 v71, v71, 0x3e0293ee, v242
	v_fmamk_f32 v72, v72, 0x3e0293ee, v242
	v_fmamk_f32 v73, v73, 0x3e0293ee, v242
	v_fmamk_f32 v74, v74, 0x3e0293ee, v242
	v_fmamk_f32 v75, v75, 0x3e0293ee, v242
	v_fmamk_f32 v76, v76, 0x3e0293ee, v242
	v_fmamk_f32 v77, v77, 0x3e0293ee, v242
	v_fmamk_f32 v78, v78, 0x3e0293ee, v242
	v_fmamk_f32 v79, v79, 0x3e0293ee, v242
	v_fmamk_f32 v80, v80, 0x3e0293ee, v242
	v_fmamk_f32 v81, v81, 0x3e0293ee, v242
	v_fmamk_f32 v82, v82, 0x3e0293ee, v242
	v_fmamk_f32 v83, v83, 0x3e0293ee, v242
	v_exp_f32_e32 v68, v68
	v_exp_f32_e32 v69, v69
	v_exp_f32_e32 v70, v70
	v_exp_f32_e32 v71, v71
	v_exp_f32_e32 v72, v72
	v_exp_f32_e32 v73, v73
	v_exp_f32_e32 v74, v74
	v_exp_f32_e32 v75, v75
	v_exp_f32_e32 v76, v76
	v_exp_f32_e32 v77, v77
	v_exp_f32_e32 v78, v78
	v_exp_f32_e32 v79, v79
	v_exp_f32_e32 v80, v80
	v_exp_f32_e32 v81, v81
	v_exp_f32_e32 v82, v82
	v_exp_f32_e32 v83, v83
	v_cvt_pk_bf16_f32 v168, v68, v69
	v_cvt_pk_bf16_f32 v169, v70, v71
	v_cvt_pk_bf16_f32 v170, v72, v73
	v_cvt_pk_bf16_f32 v171, v74, v75
	v_cvt_pk_bf16_f32 v172, v76, v77
	v_cvt_pk_bf16_f32 v173, v78, v79
	v_cvt_pk_bf16_f32 v174, v80, v81
	v_cvt_pk_bf16_f32 v175, v82, v83
	s_waitcnt lgkmcnt(0)
	s_nop 0
	v_permlane32_swap_b32_e32 v168, v170
	v_permlane32_swap_b32_e32 v169, v171
	v_permlane32_swap_b32_e32 v172, v174
	v_permlane32_swap_b32_e32 v173, v175
	s_nop 1
	v_mfma_f32_32x32x16_bf16 v[52:67], v[168:171], v[84:87], v[52:67]
	ds_read_b64_tr_b16 v[84:85], v248 offset:8192
	ds_read_b64_tr_b16 v[86:87], v248 offset:10240
	v_fmamk_f32 v210, v210, 0x3e0293ee, v249
	v_fmamk_f32 v211, v211, 0x3e0293ee, v249
	v_fmamk_f32 v212, v212, 0x3e0293ee, v249
	v_fmamk_f32 v213, v213, 0x3e0293ee, v249
	v_fmamk_f32 v214, v214, 0x3e0293ee, v249
	v_fmamk_f32 v215, v215, 0x3e0293ee, v249
	v_fmamk_f32 v216, v216, 0x3e0293ee, v249
	v_fmamk_f32 v217, v217, 0x3e0293ee, v249
	v_fmamk_f32 v218, v218, 0x3e0293ee, v249
	v_fmamk_f32 v219, v219, 0x3e0293ee, v249
	v_mfma_f32_32x32x16_bf16 v[36:51], v[168:171], v[92:95], v[36:51]
	ds_read_b64_tr_b16 v[92:93], v248 offset:8704
	ds_read_b64_tr_b16 v[94:95], v248 offset:10752
	v_fmamk_f32 v220, v220, 0x3e0293ee, v249
	v_fmamk_f32 v221, v221, 0x3e0293ee, v249
	v_fmamk_f32 v222, v222, 0x3e0293ee, v249
	v_fmamk_f32 v223, v223, 0x3e0293ee, v249
	v_fmamk_f32 v224, v224, 0x3e0293ee, v249
	v_fmamk_f32 v225, v225, 0x3e0293ee, v249
	v_exp_f32_e32 v210, v210
	v_add_f32_e32 v246, v68, v69
	v_exp_f32_e32 v211, v211
	v_add_f32_e32 v247, v70, v71
	v_mfma_f32_32x32x16_bf16 v[20:35], v[168:171], v[194:197], v[20:35]
	ds_read_b64_tr_b16 v[194:195], v248 offset:9216
	ds_read_b64_tr_b16 v[196:197], v248 offset:11264
	v_exp_f32_e32 v212, v212
	v_add_f32_e32 v246, v246, v72
	v_exp_f32_e32 v213, v213
	v_add_f32_e32 v246, v246, v73
	v_exp_f32_e32 v214, v214
	v_add_f32_e32 v247, v247, v74
	v_exp_f32_e32 v215, v215
	v_add_f32_e32 v247, v247, v75
	v_exp_f32_e32 v216, v216
	v_add_f32_e32 v246, v246, v76
	v_mfma_f32_32x32x16_bf16 v[4:19], v[168:171], v[202:205], v[4:19]
	ds_read_b64_tr_b16 v[202:203], v248 offset:9728
	ds_read_b64_tr_b16 v[204:205], v248 offset:11776
	v_exp_f32_e32 v217, v217
	v_add_f32_e32 v246, v246, v77
	v_exp_f32_e32 v218, v218
	v_add_f32_e32 v247, v247, v78
	v_exp_f32_e32 v219, v219
	v_add_f32_e32 v247, v247, v79
	v_exp_f32_e32 v220, v220
	v_add_f32_e32 v246, v246, v80
	v_exp_f32_e32 v221, v221
	v_add_f32_e32 v246, v246, v81
	v_mfma_f32_32x32x16_bf16 v[52:67], v[172:175], v[88:91], v[52:67]
	ds_read_b64_tr_b16 v[88:89], v248 offset:12288
	ds_read_b64_tr_b16 v[90:91], v248 offset:14336
	v_exp_f32_e32 v222, v222
	v_add_f32_e32 v247, v247, v82
	v_exp_f32_e32 v223, v223
	v_add_f32_e32 v247, v247, v83
	v_exp_f32_e32 v224, v224
	v_exp_f32_e32 v225, v225
	v_add_f32_e32 v246, v246, v210
	v_add_f32_e32 v246, v246, v211
	v_add_f32_e32 v247, v247, v212
	v_add_f32_e32 v247, v247, v213
	v_mfma_f32_32x32x16_bf16 v[36:51], v[172:175], v[96:99], v[36:51]
	ds_read_b64_tr_b16 v[96:97], v248 offset:12800
	ds_read_b64_tr_b16 v[98:99], v248 offset:14848
	v_add_f32_e32 v246, v246, v214
	v_add_f32_e32 v246, v246, v215
	v_add_f32_e32 v247, v247, v216
	v_add_f32_e32 v247, v247, v217
	v_add_f32_e32 v246, v246, v218
	v_add_f32_e32 v246, v246, v219
	v_add_f32_e32 v247, v247, v220
	v_add_f32_e32 v247, v247, v221
	v_add_f32_e32 v246, v246, v222
	v_add_f32_e32 v246, v246, v223
	v_mfma_f32_32x32x16_bf16 v[20:35], v[172:175], v[198:201], v[20:35]
	ds_read_b64_tr_b16 v[198:199], v248 offset:13312
	ds_read_b64_tr_b16 v[200:201], v248 offset:15360
	v_add_f32_e32 v247, v247, v224
	v_add_f32_e32 v247, v247, v225
	v_add_f32_e32 v246, v246, v247
	v_add_f32_e32 v143, v143, v246
	v_cvt_pk_bf16_f32 v68, v210, v211
	v_cvt_pk_bf16_f32 v69, v212, v213
	v_cvt_pk_bf16_f32 v70, v214, v215
	v_cvt_pk_bf16_f32 v71, v216, v217
	v_cvt_pk_bf16_f32 v72, v218, v219
	v_cvt_pk_bf16_f32 v73, v220, v221
	v_mfma_f32_32x32x16_bf16 v[4:19], v[172:175], v[206:209], v[4:19]
	ds_read_b64_tr_b16 v[206:207], v248 offset:13824
	ds_read_b64_tr_b16 v[208:209], v248 offset:15872
	v_cvt_pk_bf16_f32 v74, v222, v223
	v_cvt_pk_bf16_f32 v75, v224, v225
	v_permlane32_swap_b32_e32 v68, v70
	v_permlane32_swap_b32_e32 v69, v71
	v_permlane32_swap_b32_e32 v72, v74
	v_permlane32_swap_b32_e32 v73, v75
	s_nop 1
	s_waitcnt lgkmcnt(14)
	v_mfma_f32_32x32x16_bf16 v[52:67], v[68:71], v[84:87], v[52:67]
	s_waitcnt lgkmcnt(12)
	v_mfma_f32_32x32x16_bf16 v[36:51], v[68:71], v[92:95], v[36:51]
	s_waitcnt lgkmcnt(10)
	v_mfma_f32_32x32x16_bf16 v[20:35], v[68:71], v[194:197], v[20:35]
	s_waitcnt lgkmcnt(8)
	v_mfma_f32_32x32x16_bf16 v[4:19], v[68:71], v[202:205], v[4:19]
	s_waitcnt lgkmcnt(6)
	v_mfma_f32_32x32x16_bf16 v[52:67], v[72:75], v[88:91], v[52:67]
	s_waitcnt lgkmcnt(4)
	v_mfma_f32_32x32x16_bf16 v[36:51], v[72:75], v[96:99], v[36:51]
	s_waitcnt lgkmcnt(2)
	v_mfma_f32_32x32x16_bf16 v[20:35], v[72:75], v[198:201], v[20:35]
	s_waitcnt lgkmcnt(0)
	v_mfma_f32_32x32x16_bf16 v[4:19], v[72:75], v[206:209], v[4:19]
	s_addk_i32 s1, 0x4000
	s_add_i32 s0, s0, 1
	v_lshl_add_u64 v[134:135], v[134:135], 0, s[20:21]
	v_lshl_add_u64 v[136:137], v[136:137], 0, s[20:21]
	v_lshl_add_u64 v[138:139], v[138:139], 0, s[20:21]
	v_lshl_add_u64 v[140:141], v[140:141], 0, s[20:21]
	v_add_u32_e32 v161, 64, v161
	v_subrev_u32_e32 v162, 64, v162
	s_cmp_eq_u32 s24, s1
	s_cbranch_scc1 .LBB0_361
	s_branch .LBB0_342
